# conv2d: after each column step's wait, the next step's 4 UV rows and 6 UG rows are touched (loaded into spare registers) so the next step's loads hit in cache; otherwise v24
# baseline (speedup 1.0000x reference)
.LBB0_949:
	s_or_b64 exec, exec, s[10:11]
	v_add_co_u32_e32 v86, vcc, s63, v128
	v_pk_mul_f32 v[94:95], v[6:7], v[76:77]
	s_nop 0
	v_addc_co_u32_e32 v87, vcc, 0, v129, vcc
	flat_load_dwordx2 v[88:89], v[86:87] offset:2560
	v_lshl_add_u64 v[178:179], v[116:117], 0, s[90:91]
	v_lshl_add_u64 v[180:181], v[110:111], 0, s[90:91]
	v_lshl_add_u64 v[182:183], v[100:101], 0, s[90:91]
	global_load_dwordx2 v[184:185], v[178:179], off offset:2560
	global_load_dwordx2 v[186:187], v[180:181], off offset:2560
	global_load_dwordx2 v[188:189], v[182:183], off offset:2560
	v_pk_mul_f32 v[96:97], v[4:5], v[72:73]
	v_lshlrev_b32_e32 v62, 16, v148
	v_and_b32_e32 v63, 0xffff0000, v148
	v_lshlrev_b32_e32 v64, 16, v149
	v_and_b32_e32 v65, 0xffff0000, v149
	v_pk_mul_f32 v[106:107], v[18:19], v[80:81]
	v_pk_mul_f32 v[108:109], v[16:17], v[78:79]
	v_pk_fma_f32 v[94:95], v[2:3], v[144:145], v[94:95]
	v_pk_fma_f32 v[96:97], v[0:1], v[142:143], v[96:97]
	v_lshlrev_b32_e32 v66, 16, v152
	v_and_b32_e32 v67, 0xffff0000, v152
	v_lshlrev_b32_e32 v68, 16, v153
	v_and_b32_e32 v69, 0xffff0000, v153
	v_lshlrev_b32_e32 v70, 16, v150
	v_and_b32_e32 v71, 0xffff0000, v150
	v_lshlrev_b32_e32 v74, 16, v151
	v_and_b32_e32 v75, 0xffff0000, v151
	v_pk_mul_f32 v[148:149], v[30:31], v[84:85]
	v_pk_mul_f32 v[150:151], v[28:29], v[82:83]
	v_pk_fma_f32 v[106:107], v[14:15], v[136:137], v[106:107]
	v_pk_fma_f32 v[108:109], v[12:13], v[134:135], v[108:109]
	v_pk_fma_f32 v[94:95], v[10:11], v[64:65], v[94:95]
	v_pk_fma_f32 v[96:97], v[8:9], v[62:63], v[96:97]
	v_pk_fma_f32 v[142:143], v[26:27], v[126:127], v[148:149]
	v_pk_fma_f32 v[144:145], v[24:25], v[122:123], v[150:151]
	v_pk_fma_f32 v[106:107], v[22:23], v[68:69], v[106:107]
	v_pk_fma_f32 v[108:109], v[20:21], v[66:67], v[108:109]
	v_pk_add_f32 v[94:95], v[38:39], v[94:95]
	v_pk_add_f32 v[96:97], v[36:37], v[96:97]
	v_pk_fma_f32 v[142:143], v[34:35], v[74:75], v[142:143]
	v_pk_fma_f32 v[144:145], v[32:33], v[70:71], v[144:145]
	v_pk_add_f32 v[94:95], v[106:107], v[94:95]
	v_pk_add_f32 v[96:97], v[108:109], v[96:97]
	v_pk_add_f32 v[94:95], v[142:143], v[94:95]
	v_pk_add_f32 v[96:97], v[144:145], v[96:97]
	v_mov_b64_e32 v[128:129], s[28:29]
	v_pk_mul_f32 v[106:107], v[94:95], v[94:95]
	v_pk_mul_f32 v[108:109], v[96:97], v[96:97]
	v_pk_fma_f32 v[106:107], v[106:107], s[26:27], v[128:129] op_sel_hi:[1,0,0] neg_lo:[1,0,0] neg_hi:[1,0,0]
	v_pk_fma_f32 v[108:109], v[108:109], s[26:27], v[128:129] op_sel_hi:[1,0,0] neg_lo:[1,0,0] neg_hi:[1,0,0]
	v_pk_mul_f32 v[106:107], v[94:95], v[106:107]
	v_pk_mul_f32 v[108:109], v[96:97], v[108:109]
	v_exp_f32_e32 v106, v106
	v_exp_f32_e32 v108, v108
	v_exp_f32_e32 v109, v109
	v_exp_f32_e32 v107, v107
	v_add_co_u32_e32 v116, vcc, s63, v116
	v_pk_add_f32 v[108:109], v[108:109], 1.0 op_sel_hi:[1,0]
	v_pk_add_f32 v[106:107], v[106:107], 1.0 op_sel_hi:[1,0]
	v_rcp_f32_e32 v108, v108
	v_rcp_f32_e32 v109, v109
	v_rcp_f32_e32 v106, v106
	v_rcp_f32_e32 v107, v107
	v_addc_co_u32_e32 v117, vcc, 0, v117, vcc
	v_pk_mul_f32 v[96:97], v[96:97], v[108:109]
	v_pk_mul_f32 v[94:95], v[94:95], v[106:107]
	v_pk_mul_f32 v[108:109], v[18:19], v[84:85]
	v_pk_mul_f32 v[142:143], v[16:17], v[82:83]
	v_pk_mul_f32 v[144:145], v[30:31], v[92:93]
	v_pk_fma_f32 v[108:109], v[14:15], v[126:127], v[108:109]
	v_add_co_u32_e32 v110, vcc, s63, v110
	v_pk_fma_f32 v[108:109], v[22:23], v[74:75], v[108:109]
	s_nop 0
	v_addc_co_u32_e32 v111, vcc, 0, v111, vcc
	v_add_co_u32_e32 v100, vcc, s63, v100
	s_waitcnt vmcnt(0) lgkmcnt(0)
	v_readfirstlane_b32 s64, v86
	v_readfirstlane_b32 s65, v87
	v_and_b32_e32 v221, 63, v196
	v_lshlrev_b32_e32 v221, 3, v221
	s_nop 3
	s_add_u32 s64, s64, 0x2000
	s_addc_u32 s65, s65, 0
	global_load_dwordx2 v[198:199], v221, s[64:65]
	s_add_u32 s64, s64, 0x58000
	s_addc_u32 s65, s65, 0
	global_load_dwordx2 v[200:201], v221, s[64:65]
	s_add_u32 s64, s64, 0x58000
	s_addc_u32 s65, s65, 0
	global_load_dwordx2 v[202:203], v221, s[64:65]
	s_add_u32 s64, s64, 0x58000
	s_addc_u32 s65, s65, 0
	global_load_dwordx2 v[204:205], v221, s[64:65]
	s_sub_u32 s64, s64, 0x1615d400
	s_subb_u32 s65, s65, 0
	global_load_dwordx2 v[206:207], v221, s[64:65]
	s_add_u32 s64, s64, 0x58000
	s_addc_u32 s65, s65, 0
	global_load_dwordx2 v[208:209], v221, s[64:65]
	s_add_u32 s64, s64, 0x58000
	s_addc_u32 s65, s65, 0
	global_load_dwordx2 v[210:211], v221, s[64:65]
	s_add_u32 s64, s64, 0x58000
	s_addc_u32 s65, s65, 0
	global_load_dwordx2 v[212:213], v221, s[64:65]
	s_add_u32 s64, s64, 0x58000
	s_addc_u32 s65, s65, 0
	global_load_dwordx2 v[214:215], v221, s[64:65]
	s_add_u32 s64, s64, 0x58000
	s_addc_u32 s65, s65, 0
	global_load_dwordx2 v[216:217], v221, s[64:65]
	v_mov_b64_e32 v[148:149], v[158:159]
	v_addc_co_u32_e32 v101, vcc, 0, v101, vcc
	v_mov_b64_e32 v[152:153], v[154:155]
	v_mov_b64_e32 v[150:151], v[156:157]
	v_lshlrev_b32_e32 v43, 16, v88
	v_and_b32_e32 v88, 0xffff0000, v88
	v_lshlrev_b32_e32 v106, 16, v89
	v_and_b32_e32 v89, 0xffff0000, v89
	v_mul_f32_e32 v88, v97, v88
	v_mul_f32_e32 v89, v95, v89
	v_mul_f32_e32 v43, v96, v43
	v_mul_f32_e32 v94, v94, v106
	v_cvt_pk_bf16_f32 v88, v43, v88
	v_cvt_pk_bf16_f32 v89, v94, v89
	flat_store_dwordx2 v[86:87], v[88:89] offset:2560
	s_nop 1
	v_mov_b64_e32 v[94:95], v[184:185]
	v_pk_mul_f32 v[96:97], v[6:7], v[80:81]
	v_pk_mul_f32 v[106:107], v[4:5], v[78:79]
	v_pk_fma_f32 v[96:97], v[2:3], v[136:137], v[96:97]
	v_pk_fma_f32 v[106:107], v[0:1], v[134:135], v[106:107]
	v_lshlrev_b32_e32 v86, 16, v146
	v_and_b32_e32 v87, 0xffff0000, v146
	v_lshlrev_b32_e32 v88, 16, v147
	v_and_b32_e32 v89, 0xffff0000, v147
	v_pk_mul_f32 v[146:147], v[28:29], v[90:91]
	v_pk_fma_f32 v[134:135], v[12:13], v[122:123], v[142:143]
	v_pk_fma_f32 v[96:97], v[10:11], v[68:69], v[96:97]
	v_pk_fma_f32 v[106:107], v[8:9], v[66:67], v[106:107]
	v_pk_fma_f32 v[136:137], v[26:27], v[120:121], v[144:145]
	v_pk_fma_f32 v[142:143], v[24:25], v[118:119], v[146:147]
	v_pk_fma_f32 v[134:135], v[20:21], v[70:71], v[134:135]
	v_pk_add_f32 v[96:97], v[38:39], v[96:97]
	v_pk_add_f32 v[106:107], v[36:37], v[106:107]
	v_pk_fma_f32 v[136:137], v[34:35], v[88:89], v[136:137]
	v_pk_fma_f32 v[142:143], v[32:33], v[86:87], v[142:143]
	v_pk_add_f32 v[96:97], v[108:109], v[96:97]
	v_pk_add_f32 v[106:107], v[134:135], v[106:107]
	v_pk_add_f32 v[96:97], v[136:137], v[96:97]
	v_pk_add_f32 v[106:107], v[142:143], v[106:107]
	v_pk_mul_f32 v[108:109], v[96:97], v[96:97]
	v_pk_mul_f32 v[134:135], v[106:107], v[106:107]
	v_pk_fma_f32 v[108:109], v[108:109], s[26:27], v[128:129] op_sel_hi:[1,0,0] neg_lo:[1,0,0] neg_hi:[1,0,0]
	v_pk_fma_f32 v[134:135], v[134:135], s[26:27], v[128:129] op_sel_hi:[1,0,0] neg_lo:[1,0,0] neg_hi:[1,0,0]
	v_pk_mul_f32 v[108:109], v[96:97], v[108:109]
	v_pk_mul_f32 v[134:135], v[106:107], v[134:135]
	v_exp_f32_e32 v108, v108
	v_exp_f32_e32 v134, v134
	v_exp_f32_e32 v135, v135
	v_exp_f32_e32 v109, v109
	v_pk_mul_f32 v[136:137], v[30:31], v[102:103]
	v_pk_mul_f32 v[142:143], v[28:29], v[98:99]
	v_pk_add_f32 v[134:135], v[134:135], 1.0 op_sel_hi:[1,0]
	v_pk_add_f32 v[108:109], v[108:109], 1.0 op_sel_hi:[1,0]
	v_rcp_f32_e32 v134, v134
	v_rcp_f32_e32 v135, v135
	v_rcp_f32_e32 v108, v108
	v_rcp_f32_e32 v109, v109
	v_mov_b64_e32 v[146:147], v[160:161]
	v_pk_mul_f32 v[106:107], v[106:107], v[134:135]
	v_pk_mul_f32 v[134:135], v[16:17], v[90:91]
	v_pk_mul_f32 v[96:97], v[96:97], v[108:109]
	s_nop 0
	v_lshlrev_b32_e32 v43, 16, v94
	v_and_b32_e32 v94, 0xffff0000, v94
	v_lshlrev_b32_e32 v108, 16, v95
	v_and_b32_e32 v95, 0xffff0000, v95
	v_mul_f32_e32 v94, v107, v94
	v_mul_f32_e32 v95, v97, v95
	v_mul_f32_e32 v43, v106, v43
	v_mul_f32_e32 v96, v96, v108
	v_cvt_pk_bf16_f32 v94, v43, v94
	v_cvt_pk_bf16_f32 v95, v96, v95
	flat_store_dwordx2 v[116:117], v[94:95] offset:2560
	s_nop 1
	v_mov_b64_e32 v[106:107], v[186:187]
	v_pk_mul_f32 v[108:109], v[6:7], v[84:85]
	v_pk_mul_f32 v[116:117], v[4:5], v[82:83]
	v_lshlrev_b32_e32 v94, 16, v124
	v_and_b32_e32 v95, 0xffff0000, v124
	v_lshlrev_b32_e32 v96, 16, v125
	v_and_b32_e32 v97, 0xffff0000, v125
	v_pk_mul_f32 v[124:125], v[18:19], v[92:93]
	v_pk_fma_f32 v[108:109], v[2:3], v[126:127], v[108:109]
	v_pk_fma_f32 v[116:117], v[0:1], v[122:123], v[116:117]
	v_pk_fma_f32 v[122:123], v[14:15], v[120:121], v[124:125]
	v_pk_fma_f32 v[124:125], v[12:13], v[118:119], v[134:135]
	v_pk_fma_f32 v[108:109], v[10:11], v[74:75], v[108:109]
	v_pk_fma_f32 v[116:117], v[8:9], v[70:71], v[116:117]
	v_pk_fma_f32 v[126:127], v[26:27], v[132:133], v[136:137]
	v_pk_fma_f32 v[134:135], v[24:25], v[130:131], v[142:143]
	v_pk_fma_f32 v[122:123], v[22:23], v[88:89], v[122:123]
	v_pk_fma_f32 v[124:125], v[20:21], v[86:87], v[124:125]
	v_pk_add_f32 v[108:109], v[38:39], v[108:109]
	v_pk_add_f32 v[116:117], v[36:37], v[116:117]
	v_pk_fma_f32 v[126:127], v[34:35], v[96:97], v[126:127]
	v_pk_fma_f32 v[134:135], v[32:33], v[94:95], v[134:135]
	v_pk_add_f32 v[108:109], v[122:123], v[108:109]
	v_pk_add_f32 v[116:117], v[124:125], v[116:117]
	v_pk_add_f32 v[108:109], v[126:127], v[108:109]
	v_pk_add_f32 v[116:117], v[134:135], v[116:117]
	v_pk_mul_f32 v[122:123], v[108:109], v[108:109]
	v_pk_mul_f32 v[124:125], v[116:117], v[116:117]
	v_pk_fma_f32 v[122:123], v[122:123], s[26:27], v[128:129] op_sel_hi:[1,0,0] neg_lo:[1,0,0] neg_hi:[1,0,0]
	v_pk_fma_f32 v[124:125], v[124:125], s[26:27], v[128:129] op_sel_hi:[1,0,0] neg_lo:[1,0,0] neg_hi:[1,0,0]
	v_pk_mul_f32 v[122:123], v[108:109], v[122:123]
	v_pk_mul_f32 v[124:125], v[116:117], v[124:125]
	v_exp_f32_e32 v122, v122
	v_exp_f32_e32 v124, v124
	v_exp_f32_e32 v125, v125
	v_exp_f32_e32 v123, v123
	v_pk_mul_f32 v[126:127], v[30:31], v[114:115]
	v_pk_mul_f32 v[134:135], v[28:29], v[112:113]
	v_pk_add_f32 v[124:125], v[124:125], 1.0 op_sel_hi:[1,0]
	v_pk_add_f32 v[122:123], v[122:123], 1.0 op_sel_hi:[1,0]
	v_rcp_f32_e32 v124, v124
	v_rcp_f32_e32 v125, v125
	v_rcp_f32_e32 v122, v122
	v_rcp_f32_e32 v123, v123
	v_pk_mul_f32 v[116:117], v[116:117], v[124:125]
	v_pk_mul_f32 v[124:125], v[16:17], v[98:99]
	v_pk_mul_f32 v[108:109], v[108:109], v[122:123]
	s_nop 0
	v_lshlrev_b32_e32 v43, 16, v106
	v_and_b32_e32 v106, 0xffff0000, v106
	v_lshlrev_b32_e32 v122, 16, v107
	v_and_b32_e32 v107, 0xffff0000, v107
	v_mul_f32_e32 v106, v117, v106
	v_mul_f32_e32 v107, v109, v107
	v_mul_f32_e32 v43, v116, v43
	v_mul_f32_e32 v108, v108, v122
	v_cvt_pk_bf16_f32 v106, v43, v106
	v_cvt_pk_bf16_f32 v107, v108, v107
	flat_store_dwordx2 v[110:111], v[106:107] offset:2560
	s_nop 1
	v_mov_b64_e32 v[110:111], v[188:189]
	v_lshlrev_b32_e32 v106, 16, v104
	v_and_b32_e32 v107, 0xffff0000, v104
	v_lshlrev_b32_e32 v108, 16, v105
	v_and_b32_e32 v109, 0xffff0000, v105
	v_pk_mul_f32 v[104:105], v[6:7], v[92:93]
	v_pk_mul_f32 v[116:117], v[4:5], v[90:91]
	v_pk_mul_f32 v[122:123], v[18:19], v[102:103]
	v_pk_fma_f32 v[104:105], v[2:3], v[120:121], v[104:105]
	v_pk_fma_f32 v[116:117], v[0:1], v[118:119], v[116:117]
	v_pk_fma_f32 v[118:119], v[14:15], v[132:133], v[122:123]
	v_pk_fma_f32 v[104:105], v[10:11], v[88:89], v[104:105]
	v_pk_fma_f32 v[120:121], v[12:13], v[130:131], v[124:125]
	v_pk_fma_f32 v[122:123], v[26:27], v[140:141], v[126:127]
	v_pk_fma_f32 v[116:117], v[8:9], v[86:87], v[116:117]
	v_pk_fma_f32 v[118:119], v[22:23], v[96:97], v[118:119]
	v_pk_add_f32 v[104:105], v[38:39], v[104:105]
	v_pk_fma_f32 v[124:125], v[24:25], v[138:139], v[134:135]
	v_pk_fma_f32 v[120:121], v[20:21], v[94:95], v[120:121]
	v_pk_fma_f32 v[122:123], v[34:35], v[108:109], v[122:123]
	v_pk_add_f32 v[116:117], v[36:37], v[116:117]
	v_pk_add_f32 v[104:105], v[118:119], v[104:105]
	v_pk_fma_f32 v[124:125], v[32:33], v[106:107], v[124:125]
	v_pk_add_f32 v[116:117], v[120:121], v[116:117]
	v_pk_add_f32 v[104:105], v[122:123], v[104:105]
	v_pk_add_f32 v[116:117], v[124:125], v[116:117]
	v_pk_mul_f32 v[118:119], v[104:105], v[104:105]
	v_pk_mul_f32 v[120:121], v[116:117], v[116:117]
	v_pk_fma_f32 v[118:119], v[118:119], s[26:27], v[128:129] op_sel_hi:[1,0,0] neg_lo:[1,0,0] neg_hi:[1,0,0]
	v_pk_fma_f32 v[120:121], v[120:121], s[26:27], v[128:129] op_sel_hi:[1,0,0] neg_lo:[1,0,0] neg_hi:[1,0,0]
	v_pk_mul_f32 v[118:119], v[104:105], v[118:119]
	v_pk_mul_f32 v[120:121], v[116:117], v[120:121]
	v_exp_f32_e32 v118, v118
	v_exp_f32_e32 v119, v119
	v_exp_f32_e32 v120, v120
	v_exp_f32_e32 v121, v121
	v_mov_b64_e32 v[124:125], v[162:163]
	v_pk_add_f32 v[118:119], v[118:119], 1.0 op_sel_hi:[1,0]
	v_pk_add_f32 v[120:121], v[120:121], 1.0 op_sel_hi:[1,0]
	v_rcp_f32_e32 v118, v118
	v_rcp_f32_e32 v119, v119
	v_rcp_f32_e32 v120, v120
	v_rcp_f32_e32 v121, v121
	v_pk_mul_f32 v[104:105], v[104:105], v[118:119]
	v_pk_mul_f32 v[116:117], v[116:117], v[120:121]
	s_nop 0
	v_lshlrev_b32_e32 v118, 16, v111
	v_and_b32_e32 v111, 0xffff0000, v111
	v_lshlrev_b32_e32 v43, 16, v110
	v_and_b32_e32 v110, 0xffff0000, v110
	v_mul_f32_e32 v105, v105, v111
	v_mul_f32_e32 v43, v116, v43
	v_mul_f32_e32 v110, v117, v110
	v_mul_f32_e32 v116, v104, v118
	v_cvt_pk_bf16_f32 v104, v43, v110
	v_cvt_pk_bf16_f32 v105, v116, v105
	flat_store_dwordx2 v[100:101], v[104:105] offset:2560
	v_mov_b64_e32 v[104:105], v[164:165]

.LBB0_959:
	s_or_b64 exec, exec, s[10:11]
	v_add_co_u32_e32 v130, vcc, s61, v128
	v_lshlrev_b32_e32 v142, 16, v118
	s_nop 0
	v_addc_co_u32_e32 v131, vcc, 0, v129, vcc
	flat_load_dwordx2 v[138:139], v[130:131] offset:3584
	v_lshl_add_u64 v[178:179], v[116:117], 0, s[88:89]
	v_lshl_add_u64 v[180:181], v[110:111], 0, s[88:89]
	v_lshl_add_u64 v[182:183], v[100:101], 0, s[88:89]
	global_load_dwordx2 v[184:185], v[178:179], off offset:3584
	global_load_dwordx2 v[186:187], v[180:181], off offset:3584
	global_load_dwordx2 v[188:189], v[182:183], off offset:3584
	v_and_b32_e32 v143, 0xffff0000, v118
	v_lshlrev_b32_e32 v144, 16, v119
	v_and_b32_e32 v145, 0xffff0000, v119
	v_pk_mul_f32 v[118:119], v[6:7], v[64:65]
	v_pk_mul_f32 v[156:157], v[4:5], v[62:63]
	v_pk_mul_f32 v[158:159], v[18:19], v[68:69]
	v_pk_fma_f32 v[118:119], v[2:3], v[76:77], v[118:119]
	v_lshlrev_b32_e32 v136, 16, v123
	v_and_b32_e32 v137, 0xffff0000, v123
	v_pk_mul_f32 v[160:161], v[16:17], v[66:67]
	v_pk_mul_f32 v[162:163], v[30:31], v[74:75]
	v_pk_fma_f32 v[156:157], v[0:1], v[72:73], v[156:157]
	v_pk_fma_f32 v[158:159], v[14:15], v[80:81], v[158:159]
	v_pk_fma_f32 v[118:119], v[10:11], v[144:145], v[118:119]
	v_lshlrev_b32_e32 v134, 16, v122
	v_and_b32_e32 v135, 0xffff0000, v122
	v_lshlrev_b32_e32 v122, 16, v126
	v_and_b32_e32 v123, 0xffff0000, v126
	v_lshlrev_b32_e32 v126, 16, v127
	v_and_b32_e32 v127, 0xffff0000, v127
	v_pk_mul_f32 v[164:165], v[28:29], v[70:71]
	v_pk_fma_f32 v[160:161], v[12:13], v[78:79], v[160:161]
	v_pk_fma_f32 v[162:163], v[26:27], v[84:85], v[162:163]
	v_pk_fma_f32 v[156:157], v[8:9], v[142:143], v[156:157]
	v_pk_fma_f32 v[158:159], v[22:23], v[136:137], v[158:159]
	v_pk_add_f32 v[118:119], v[38:39], v[118:119]
	v_pk_fma_f32 v[164:165], v[24:25], v[82:83], v[164:165]
	v_pk_fma_f32 v[160:161], v[20:21], v[134:135], v[160:161]
	v_pk_fma_f32 v[162:163], v[34:35], v[126:127], v[162:163]
	v_pk_add_f32 v[156:157], v[36:37], v[156:157]
	v_pk_add_f32 v[118:119], v[118:119], v[158:159]
	v_pk_fma_f32 v[164:165], v[32:33], v[122:123], v[164:165]
	v_pk_add_f32 v[156:157], v[156:157], v[160:161]
	v_pk_add_f32 v[118:119], v[118:119], v[162:163]
	v_mov_b64_e32 v[154:155], s[28:29]
	v_pk_add_f32 v[156:157], v[156:157], v[164:165]
	v_pk_mul_f32 v[158:159], v[118:119], v[118:119]
	v_pk_mul_f32 v[160:161], v[156:157], v[156:157]
	v_pk_fma_f32 v[158:159], v[158:159], s[26:27], v[154:155] op_sel_hi:[1,0,0] neg_lo:[1,0,0] neg_hi:[1,0,0]
	v_pk_fma_f32 v[160:161], v[160:161], s[26:27], v[154:155] op_sel_hi:[1,0,0] neg_lo:[1,0,0] neg_hi:[1,0,0]
	v_pk_mul_f32 v[158:159], v[118:119], v[158:159]
	v_pk_mul_f32 v[160:161], v[156:157], v[160:161]
	v_exp_f32_e32 v158, v158
	v_exp_f32_e32 v159, v159
	v_exp_f32_e32 v160, v160
	v_exp_f32_e32 v161, v161
	v_add_co_u32_e32 v162, vcc, s61, v116
	v_pk_add_f32 v[158:159], v[158:159], 1.0 op_sel_hi:[1,0]
	v_pk_add_f32 v[160:161], v[160:161], 1.0 op_sel_hi:[1,0]
	v_rcp_f32_e32 v158, v158
	v_rcp_f32_e32 v159, v159
	v_rcp_f32_e32 v160, v160
	v_rcp_f32_e32 v161, v161
	v_addc_co_u32_e32 v163, vcc, 0, v117, vcc
	v_pk_mul_f32 v[118:119], v[118:119], v[158:159]
	v_pk_mul_f32 v[156:157], v[156:157], v[160:161]
	v_pk_mul_f32 v[160:161], v[16:17], v[70:71]
	v_pk_mul_f32 v[164:165], v[30:31], v[88:89]
	v_pk_mul_f32 v[170:171], v[28:29], v[86:87]
	v_pk_fma_f32 v[160:161], v[12:13], v[82:83], v[160:161]
	v_pk_fma_f32 v[170:171], v[24:25], v[90:91], v[170:171]
	v_pk_fma_f32 v[164:165], v[26:27], v[92:93], v[164:165]
	v_pk_fma_f32 v[160:161], v[20:21], v[122:123], v[160:161]
	v_pk_mul_f32 v[172:173], v[28:29], v[94:95]
	v_pk_mul_f32 v[174:175], v[28:29], v[106:107]
	v_pk_fma_f32 v[172:173], v[24:25], v[98:99], v[172:173]
	v_pk_fma_f32 v[174:175], v[24:25], v[112:113], v[174:175]
	s_waitcnt vmcnt(0) lgkmcnt(0)
	v_readfirstlane_b32 s64, v130
	v_readfirstlane_b32 s65, v131
	v_and_b32_e32 v221, 63, v196
	v_lshlrev_b32_e32 v221, 3, v221
	s_nop 3
	s_add_u32 s64, s64, 0x2400
	s_addc_u32 s65, s65, 0
	global_load_dwordx2 v[198:199], v221, s[64:65]
	s_add_u32 s64, s64, 0x58000
	s_addc_u32 s65, s65, 0
	global_load_dwordx2 v[200:201], v221, s[64:65]
	s_add_u32 s64, s64, 0x58000
	s_addc_u32 s65, s65, 0
	global_load_dwordx2 v[202:203], v221, s[64:65]
	s_add_u32 s64, s64, 0x58000
	s_addc_u32 s65, s65, 0
	global_load_dwordx2 v[204:205], v221, s[64:65]
	s_sub_u32 s64, s64, 0x1615d400
	s_subb_u32 s65, s65, 0
	global_load_dwordx2 v[206:207], v221, s[64:65]
	s_add_u32 s64, s64, 0x58000
	s_addc_u32 s65, s65, 0
	global_load_dwordx2 v[208:209], v221, s[64:65]
	s_add_u32 s64, s64, 0x58000
	s_addc_u32 s65, s65, 0
	global_load_dwordx2 v[210:211], v221, s[64:65]
	s_add_u32 s64, s64, 0x58000
	s_addc_u32 s65, s65, 0
	global_load_dwordx2 v[212:213], v221, s[64:65]
	s_add_u32 s64, s64, 0x58000
	s_addc_u32 s65, s65, 0
	global_load_dwordx2 v[214:215], v221, s[64:65]
	s_add_u32 s64, s64, 0x58000
	s_addc_u32 s65, s65, 0
	global_load_dwordx2 v[216:217], v221, s[64:65]
	v_lshlrev_b32_e32 v158, 16, v139
	v_and_b32_e32 v139, 0xffff0000, v139
	v_lshlrev_b32_e32 v43, 16, v138
	v_and_b32_e32 v138, 0xffff0000, v138
	v_mul_f32_e32 v119, v119, v139
	v_mul_f32_e32 v43, v156, v43
	v_mul_f32_e32 v138, v157, v138
	v_mul_f32_e32 v156, v118, v158
	v_cvt_pk_bf16_f32 v118, v43, v138
	v_cvt_pk_bf16_f32 v119, v156, v119
	flat_store_dwordx2 v[130:131], v[118:119] offset:3584
	s_nop 1
	v_mov_b64_e32 v[130:131], v[184:185]
	v_pk_mul_f32 v[138:139], v[6:7], v[68:69]
	v_pk_mul_f32 v[156:157], v[4:5], v[66:67]
	v_pk_mul_f32 v[158:159], v[18:19], v[74:75]
	v_pk_fma_f32 v[156:157], v[0:1], v[78:79], v[156:157]
	v_pk_fma_f32 v[138:139], v[2:3], v[80:81], v[138:139]
	v_pk_fma_f32 v[158:159], v[14:15], v[84:85], v[158:159]
	v_pk_fma_f32 v[138:139], v[10:11], v[136:137], v[138:139]
	v_pk_fma_f32 v[156:157], v[8:9], v[134:135], v[156:157]
	v_lshlrev_b32_e32 v118, 16, v120
	v_and_b32_e32 v119, 0xffff0000, v120
	v_lshlrev_b32_e32 v120, 16, v121
	v_and_b32_e32 v121, 0xffff0000, v121
	v_pk_fma_f32 v[158:159], v[22:23], v[126:127], v[158:159]
	v_pk_add_f32 v[156:157], v[36:37], v[156:157]
	v_pk_add_f32 v[138:139], v[38:39], v[138:139]
	v_pk_fma_f32 v[164:165], v[34:35], v[120:121], v[164:165]
	v_pk_fma_f32 v[170:171], v[32:33], v[118:119], v[170:171]
	v_pk_add_f32 v[138:139], v[138:139], v[158:159]
	v_pk_add_f32 v[156:157], v[156:157], v[160:161]
	v_pk_add_f32 v[138:139], v[138:139], v[164:165]
	v_pk_add_f32 v[156:157], v[156:157], v[170:171]
	v_pk_mul_f32 v[158:159], v[138:139], v[138:139]
	v_pk_mul_f32 v[160:161], v[156:157], v[156:157]
	v_pk_fma_f32 v[158:159], v[158:159], s[26:27], v[154:155] op_sel_hi:[1,0,0] neg_lo:[1,0,0] neg_hi:[1,0,0]
	v_pk_fma_f32 v[160:161], v[160:161], s[26:27], v[154:155] op_sel_hi:[1,0,0] neg_lo:[1,0,0] neg_hi:[1,0,0]
	v_pk_mul_f32 v[158:159], v[138:139], v[158:159]
	v_pk_mul_f32 v[160:161], v[156:157], v[160:161]
	v_exp_f32_e32 v158, v158
	v_exp_f32_e32 v160, v160
	v_exp_f32_e32 v161, v161
	v_exp_f32_e32 v159, v159
	v_add_co_u32_e32 v164, vcc, s61, v110
	v_pk_add_f32 v[160:161], v[160:161], 1.0 op_sel_hi:[1,0]
	v_pk_add_f32 v[158:159], v[158:159], 1.0 op_sel_hi:[1,0]
	v_rcp_f32_e32 v160, v160
	v_rcp_f32_e32 v161, v161
	v_rcp_f32_e32 v158, v158
	v_rcp_f32_e32 v159, v159
	v_addc_co_u32_e32 v165, vcc, 0, v111, vcc
	v_pk_mul_f32 v[156:157], v[156:157], v[160:161]
	v_pk_mul_f32 v[138:139], v[138:139], v[158:159]
	v_pk_mul_f32 v[160:161], v[18:19], v[88:89]
	v_pk_mul_f32 v[170:171], v[30:31], v[96:97]
	v_pk_fma_f32 v[160:161], v[14:15], v[92:93], v[160:161]
	v_pk_fma_f32 v[170:171], v[26:27], v[102:103], v[170:171]
	v_pk_fma_f32 v[160:161], v[22:23], v[120:121], v[160:161]
	s_nop 0
	v_lshlrev_b32_e32 v43, 16, v130
	v_and_b32_e32 v130, 0xffff0000, v130
	v_lshlrev_b32_e32 v158, 16, v131
	v_and_b32_e32 v131, 0xffff0000, v131
	v_mul_f32_e32 v130, v157, v130
	v_mul_f32_e32 v131, v139, v131
	v_mul_f32_e32 v43, v156, v43
	v_mul_f32_e32 v138, v138, v158
	v_cvt_pk_bf16_f32 v130, v43, v130
	v_cvt_pk_bf16_f32 v131, v138, v131
	flat_store_dwordx2 v[162:163], v[130:131] offset:3584
	s_nop 1
	v_mov_b64_e32 v[138:139], v[186:187]
	v_pk_mul_f32 v[156:157], v[6:7], v[74:75]
	v_pk_mul_f32 v[158:159], v[4:5], v[70:71]
	v_pk_mul_f32 v[162:163], v[16:17], v[86:87]
	v_pk_fma_f32 v[158:159], v[0:1], v[82:83], v[158:159]
	v_pk_fma_f32 v[156:157], v[2:3], v[84:85], v[156:157]
	v_pk_fma_f32 v[162:163], v[12:13], v[90:91], v[162:163]
	v_pk_fma_f32 v[156:157], v[10:11], v[126:127], v[156:157]
	v_pk_fma_f32 v[158:159], v[8:9], v[122:123], v[158:159]
	v_lshlrev_b32_e32 v130, 16, v132
	v_and_b32_e32 v131, 0xffff0000, v132
	v_lshlrev_b32_e32 v132, 16, v133
	v_and_b32_e32 v133, 0xffff0000, v133
	v_pk_fma_f32 v[162:163], v[20:21], v[118:119], v[162:163]
	v_pk_add_f32 v[158:159], v[36:37], v[158:159]
	v_pk_add_f32 v[156:157], v[38:39], v[156:157]
	v_pk_fma_f32 v[170:171], v[34:35], v[132:133], v[170:171]
	v_pk_fma_f32 v[172:173], v[32:33], v[130:131], v[172:173]
	v_pk_add_f32 v[156:157], v[156:157], v[160:161]
	v_pk_add_f32 v[158:159], v[158:159], v[162:163]
	v_pk_add_f32 v[156:157], v[156:157], v[170:171]
	v_pk_add_f32 v[158:159], v[158:159], v[172:173]
	v_pk_mul_f32 v[160:161], v[156:157], v[156:157]
	v_pk_mul_f32 v[162:163], v[158:159], v[158:159]
	v_pk_fma_f32 v[160:161], v[160:161], s[26:27], v[154:155] op_sel_hi:[1,0,0] neg_lo:[1,0,0] neg_hi:[1,0,0]
	v_pk_fma_f32 v[162:163], v[162:163], s[26:27], v[154:155] op_sel_hi:[1,0,0] neg_lo:[1,0,0] neg_hi:[1,0,0]
	v_pk_mul_f32 v[160:161], v[156:157], v[160:161]
	v_pk_mul_f32 v[162:163], v[158:159], v[162:163]
	v_exp_f32_e32 v160, v160
	v_exp_f32_e32 v162, v162
	v_exp_f32_e32 v163, v163
	v_exp_f32_e32 v161, v161
	v_add_co_u32_e32 v170, vcc, s61, v100
	v_pk_add_f32 v[162:163], v[162:163], 1.0 op_sel_hi:[1,0]
	v_pk_add_f32 v[160:161], v[160:161], 1.0 op_sel_hi:[1,0]
	v_rcp_f32_e32 v162, v162
	v_rcp_f32_e32 v163, v163
	v_rcp_f32_e32 v160, v160
	v_rcp_f32_e32 v161, v161
	v_addc_co_u32_e32 v171, vcc, 0, v101, vcc
	v_pk_mul_f32 v[158:159], v[158:159], v[162:163]
	v_pk_mul_f32 v[156:157], v[156:157], v[160:161]
	v_pk_mul_f32 v[162:163], v[18:19], v[96:97]
	v_pk_mul_f32 v[172:173], v[30:31], v[108:109]
	v_pk_fma_f32 v[162:163], v[14:15], v[102:103], v[162:163]
	v_pk_fma_f32 v[172:173], v[26:27], v[114:115], v[172:173]
	v_pk_fma_f32 v[162:163], v[22:23], v[132:133], v[162:163]
	s_nop 0
	v_lshlrev_b32_e32 v43, 16, v138
	v_and_b32_e32 v138, 0xffff0000, v138
	v_lshlrev_b32_e32 v160, 16, v139
	v_and_b32_e32 v139, 0xffff0000, v139
	v_mul_f32_e32 v138, v159, v138
	v_mul_f32_e32 v139, v157, v139
	v_mul_f32_e32 v43, v158, v43
	v_mul_f32_e32 v156, v156, v160
	v_cvt_pk_bf16_f32 v138, v43, v138
	v_cvt_pk_bf16_f32 v139, v156, v139
	flat_store_dwordx2 v[164:165], v[138:139] offset:3584
	s_nop 1
	v_mov_b64_e32 v[156:157], v[188:189]
	v_pk_mul_f32 v[158:159], v[6:7], v[88:89]
	v_pk_mul_f32 v[160:161], v[4:5], v[86:87]
	v_pk_mul_f32 v[164:165], v[16:17], v[94:95]
	v_pk_fma_f32 v[160:161], v[0:1], v[90:91], v[160:161]
	v_pk_fma_f32 v[158:159], v[2:3], v[92:93], v[158:159]
	v_pk_fma_f32 v[164:165], v[12:13], v[98:99], v[164:165]
	v_pk_fma_f32 v[158:159], v[10:11], v[120:121], v[158:159]
	v_pk_fma_f32 v[160:161], v[8:9], v[118:119], v[160:161]
	v_lshlrev_b32_e32 v138, 16, v140
	v_and_b32_e32 v139, 0xffff0000, v140
	v_lshlrev_b32_e32 v140, 16, v141
	v_and_b32_e32 v141, 0xffff0000, v141
	v_pk_fma_f32 v[164:165], v[20:21], v[130:131], v[164:165]
	v_pk_add_f32 v[160:161], v[36:37], v[160:161]
	v_pk_add_f32 v[158:159], v[38:39], v[158:159]
	v_pk_fma_f32 v[172:173], v[34:35], v[140:141], v[172:173]
	v_pk_fma_f32 v[174:175], v[32:33], v[138:139], v[174:175]
	v_pk_add_f32 v[158:159], v[158:159], v[162:163]
	v_pk_add_f32 v[160:161], v[160:161], v[164:165]
	v_pk_add_f32 v[158:159], v[158:159], v[172:173]
	v_pk_add_f32 v[160:161], v[160:161], v[174:175]
	v_pk_mul_f32 v[162:163], v[158:159], v[158:159]
	v_pk_mul_f32 v[164:165], v[160:161], v[160:161]
	v_add_u32_e32 v43, 1, v168
	v_pk_fma_f32 v[164:165], v[164:165], s[26:27], v[154:155] op_sel_hi:[1,0,0] neg_lo:[1,0,0] neg_hi:[1,0,0]
	v_pk_fma_f32 v[154:155], v[162:163], s[26:27], v[154:155] op_sel_hi:[1,0,0] neg_lo:[1,0,0] neg_hi:[1,0,0]
	v_pk_mul_f32 v[162:163], v[160:161], v[164:165]
	v_pk_mul_f32 v[154:155], v[158:159], v[154:155]
	v_exp_f32_e32 v162, v162
	v_exp_f32_e32 v154, v154
	v_exp_f32_e32 v155, v155
	v_exp_f32_e32 v163, v163
	v_cmp_lt_u32_e32 vcc, v43, v53
	v_pk_add_f32 v[154:155], v[154:155], 1.0 op_sel_hi:[1,0]
	v_pk_add_f32 v[162:163], v[162:163], 1.0 op_sel_hi:[1,0]
	v_rcp_f32_e32 v154, v154
	v_rcp_f32_e32 v155, v155
	v_rcp_f32_e32 v162, v162
	v_rcp_f32_e32 v163, v163
	v_pk_mul_f32 v[154:155], v[158:159], v[154:155]
	v_pk_mul_f32 v[160:161], v[160:161], v[162:163]
	s_nop 0
	v_lshlrev_b32_e32 v159, 16, v157
	v_and_b32_e32 v157, 0xffff0000, v157
	v_lshlrev_b32_e32 v158, 16, v156
	v_and_b32_e32 v156, 0xffff0000, v156
	v_mul_f32_e32 v155, v155, v157
	v_mul_f32_e32 v158, v160, v158
	v_mul_f32_e32 v156, v161, v156
	v_mul_f32_e32 v159, v154, v159
	v_cvt_pk_bf16_f32 v154, v158, v156
	v_cvt_pk_bf16_f32 v155, v159, v155
	flat_store_dwordx2 v[170:171], v[154:155] offset:3584
	s_and_saveexec_b64 s[36:37], vcc
	s_cbranch_execz .LBB0_969
	v_cmp_gt_u32_e64 s[10:11], 61, v168
	v_mov_b32_e32 v154, v42
	v_mov_b32_e32 v155, v42
	s_and_b64 s[4:5], s[6:7], s[10:11]
	v_mov_b64_e32 v[158:159], v[154:155]
	s_and_saveexec_b64 s[46:47], s[4:5]
	s_cbranch_execz .LBB0_962
	v_add_u32_e32 v43, s34, v52
	v_add_u32_e32 v72, 0xfffac200, v43
	v_mov_b32_e32 v73, v42
	v_lshl_add_u64 v[72:73], v[44:45], 0, v[72:73]
	flat_load_dwordx2 v[158:159], v[72:73]

.LBB0_968:
	s_or_b64 exec, exec, s[10:11]
	v_add_co_u32_e32 v90, vcc, s62, v128
	v_pk_mul_f32 v[98:99], v[2:3], v[64:65]
	s_nop 0
	v_addc_co_u32_e32 v91, vcc, 0, v129, vcc
	flat_load_dwordx2 v[92:93], v[90:91] offset:1024
	v_lshl_add_u64 v[178:179], v[116:117], 0, s[90:91]
	v_lshl_add_u64 v[180:181], v[110:111], 0, s[90:91]
	v_lshl_add_u64 v[182:183], v[100:101], 0, s[90:91]
	global_load_dwordx2 v[184:185], v[178:179], off offset:-3072
	global_load_dwordx2 v[186:187], v[180:181], off offset:-3072
	global_load_dwordx2 v[188:189], v[182:183], off offset:-3072
	v_pk_mul_f32 v[102:103], v[0:1], v[62:63]
	v_lshlrev_b32_e32 v72, 16, v148
	v_and_b32_e32 v73, 0xffff0000, v148
	v_lshlrev_b32_e32 v76, 16, v149
	v_and_b32_e32 v77, 0xffff0000, v149
	v_pk_mul_f32 v[112:113], v[14:15], v[68:69]
	v_pk_mul_f32 v[114:115], v[12:13], v[66:67]
	v_pk_fma_f32 v[98:99], v[6:7], v[144:145], v[98:99]
	v_pk_fma_f32 v[102:103], v[4:5], v[142:143], v[102:103]
	v_lshlrev_b32_e32 v78, 16, v152
	v_and_b32_e32 v79, 0xffff0000, v152
	v_lshlrev_b32_e32 v80, 16, v153
	v_and_b32_e32 v81, 0xffff0000, v153
	v_pk_mul_f32 v[148:149], v[26:27], v[74:75]
	v_pk_mul_f32 v[152:153], v[24:25], v[70:71]
	v_pk_fma_f32 v[112:113], v[18:19], v[136:137], v[112:113]
	v_pk_fma_f32 v[114:115], v[16:17], v[134:135], v[114:115]
	v_pk_fma_f32 v[98:99], v[10:11], v[76:77], v[98:99]
	v_pk_fma_f32 v[102:103], v[8:9], v[72:73], v[102:103]
	v_lshlrev_b32_e32 v82, 16, v150
	v_and_b32_e32 v83, 0xffff0000, v150
	v_lshlrev_b32_e32 v84, 16, v151
	v_and_b32_e32 v85, 0xffff0000, v151
	v_pk_fma_f32 v[148:149], v[30:31], v[126:127], v[148:149]
	v_pk_fma_f32 v[152:153], v[28:29], v[122:123], v[152:153]
	v_pk_fma_f32 v[112:113], v[22:23], v[80:81], v[112:113]
	v_pk_fma_f32 v[114:115], v[20:21], v[78:79], v[114:115]
	v_pk_add_f32 v[98:99], v[38:39], v[98:99]
	v_pk_add_f32 v[102:103], v[36:37], v[102:103]
	v_pk_fma_f32 v[148:149], v[34:35], v[84:85], v[148:149]
	v_pk_fma_f32 v[152:153], v[32:33], v[82:83], v[152:153]
	v_pk_add_f32 v[98:99], v[98:99], v[112:113]
	v_pk_add_f32 v[102:103], v[102:103], v[114:115]
	v_pk_add_f32 v[98:99], v[98:99], v[148:149]
	v_pk_add_f32 v[102:103], v[102:103], v[152:153]
	v_mov_b64_e32 v[150:151], s[28:29]
	v_pk_mul_f32 v[112:113], v[98:99], v[98:99]
	v_pk_mul_f32 v[114:115], v[102:103], v[102:103]
	v_pk_fma_f32 v[112:113], v[112:113], s[26:27], v[150:151] op_sel_hi:[1,0,0] neg_lo:[1,0,0] neg_hi:[1,0,0]
	v_pk_fma_f32 v[114:115], v[114:115], s[26:27], v[150:151] op_sel_hi:[1,0,0] neg_lo:[1,0,0] neg_hi:[1,0,0]
	v_pk_mul_f32 v[112:113], v[98:99], v[112:113]
	v_pk_mul_f32 v[114:115], v[102:103], v[114:115]
	v_exp_f32_e32 v112, v112
	v_exp_f32_e32 v114, v114
	v_exp_f32_e32 v115, v115
	v_exp_f32_e32 v113, v113
	v_add_co_u32_e32 v148, vcc, s62, v116
	v_pk_add_f32 v[114:115], v[114:115], 1.0 op_sel_hi:[1,0]
	v_pk_add_f32 v[112:113], v[112:113], 1.0 op_sel_hi:[1,0]
	v_rcp_f32_e32 v114, v114
	v_rcp_f32_e32 v115, v115
	v_rcp_f32_e32 v112, v112
	v_rcp_f32_e32 v113, v113
	v_addc_co_u32_e32 v149, vcc, 0, v117, vcc
	v_pk_mul_f32 v[102:103], v[102:103], v[114:115]
	v_pk_mul_f32 v[98:99], v[98:99], v[112:113]
	v_pk_mul_f32 v[114:115], v[14:15], v[74:75]
	v_pk_mul_f32 v[152:153], v[26:27], v[88:89]
	v_pk_mul_f32 v[170:171], v[24:25], v[86:87]
	v_pk_fma_f32 v[114:115], v[18:19], v[126:127], v[114:115]
	v_pk_fma_f32 v[152:153], v[30:31], v[120:121], v[152:153]
	v_pk_fma_f32 v[170:171], v[28:29], v[118:119], v[170:171]
	v_pk_fma_f32 v[114:115], v[22:23], v[84:85], v[114:115]
	v_pk_mul_f32 v[172:173], v[24:25], v[94:95]
	v_pk_mul_f32 v[174:175], v[26:27], v[108:109]
	v_pk_fma_f32 v[172:173], v[28:29], v[130:131], v[172:173]
	v_pk_mul_f32 v[176:177], v[24:25], v[106:107]
	s_waitcnt vmcnt(0) lgkmcnt(0)
	v_readfirstlane_b32 s64, v90
	v_readfirstlane_b32 s65, v91
	v_and_b32_e32 v221, 63, v196
	v_lshlrev_b32_e32 v221, 3, v221
	s_nop 3
	s_add_u32 s64, s64, 0x1a00
	s_addc_u32 s65, s65, 0
	global_load_dwordx2 v[198:199], v221, s[64:65]
	s_add_u32 s64, s64, 0x58000
	s_addc_u32 s65, s65, 0
	global_load_dwordx2 v[200:201], v221, s[64:65]
	s_add_u32 s64, s64, 0x58000
	s_addc_u32 s65, s65, 0
	global_load_dwordx2 v[202:203], v221, s[64:65]
	s_add_u32 s64, s64, 0x58000
	s_addc_u32 s65, s65, 0
	global_load_dwordx2 v[204:205], v221, s[64:65]
	s_sub_u32 s64, s64, 0x1615d400
	s_subb_u32 s65, s65, 0
	global_load_dwordx2 v[206:207], v221, s[64:65]
	s_add_u32 s64, s64, 0x58000
	s_addc_u32 s65, s65, 0
	global_load_dwordx2 v[208:209], v221, s[64:65]
	s_add_u32 s64, s64, 0x58000
	s_addc_u32 s65, s65, 0
	global_load_dwordx2 v[210:211], v221, s[64:65]
	s_add_u32 s64, s64, 0x58000
	s_addc_u32 s65, s65, 0
	global_load_dwordx2 v[212:213], v221, s[64:65]
	s_add_u32 s64, s64, 0x58000
	s_addc_u32 s65, s65, 0
	global_load_dwordx2 v[214:215], v221, s[64:65]
	s_add_u32 s64, s64, 0x58000
	s_addc_u32 s65, s65, 0
	global_load_dwordx2 v[216:217], v221, s[64:65]
	v_lshlrev_b32_e32 v43, 16, v92
	v_and_b32_e32 v92, 0xffff0000, v92
	v_lshlrev_b32_e32 v112, 16, v93
	v_and_b32_e32 v93, 0xffff0000, v93
	v_mul_f32_e32 v92, v103, v92
	v_mul_f32_e32 v93, v99, v93
	v_mul_f32_e32 v43, v102, v43
	v_mul_f32_e32 v98, v98, v112
	v_cvt_pk_bf16_f32 v92, v43, v92
	v_cvt_pk_bf16_f32 v93, v98, v93
	flat_store_dwordx2 v[90:91], v[92:93] offset:1024
	s_nop 1
	v_mov_b64_e32 v[98:99], v[184:185]
	v_pk_mul_f32 v[102:103], v[2:3], v[68:69]
	v_pk_mul_f32 v[112:113], v[0:1], v[66:67]
	v_lshlrev_b32_e32 v90, 16, v146
	v_and_b32_e32 v91, 0xffff0000, v146
	v_lshlrev_b32_e32 v92, 16, v147
	v_and_b32_e32 v93, 0xffff0000, v147
	v_pk_mul_f32 v[146:147], v[12:13], v[70:71]
	v_pk_fma_f32 v[102:103], v[6:7], v[136:137], v[102:103]
	v_pk_fma_f32 v[112:113], v[4:5], v[134:135], v[112:113]
	v_pk_fma_f32 v[146:147], v[16:17], v[122:123], v[146:147]
	v_pk_fma_f32 v[102:103], v[10:11], v[80:81], v[102:103]
	v_pk_fma_f32 v[112:113], v[8:9], v[78:79], v[112:113]
	v_pk_fma_f32 v[146:147], v[20:21], v[82:83], v[146:147]
	v_pk_add_f32 v[102:103], v[38:39], v[102:103]
	v_pk_add_f32 v[112:113], v[36:37], v[112:113]
	v_pk_fma_f32 v[152:153], v[34:35], v[92:93], v[152:153]
	v_pk_fma_f32 v[170:171], v[32:33], v[90:91], v[170:171]
	v_pk_add_f32 v[102:103], v[102:103], v[114:115]
	v_pk_add_f32 v[112:113], v[112:113], v[146:147]
	v_pk_add_f32 v[102:103], v[102:103], v[152:153]
	v_pk_add_f32 v[112:113], v[112:113], v[170:171]
	v_pk_mul_f32 v[114:115], v[102:103], v[102:103]
	v_pk_mul_f32 v[146:147], v[112:113], v[112:113]
	v_pk_fma_f32 v[114:115], v[114:115], s[26:27], v[150:151] op_sel_hi:[1,0,0] neg_lo:[1,0,0] neg_hi:[1,0,0]
	v_pk_fma_f32 v[146:147], v[146:147], s[26:27], v[150:151] op_sel_hi:[1,0,0] neg_lo:[1,0,0] neg_hi:[1,0,0]
	v_pk_mul_f32 v[114:115], v[102:103], v[114:115]
	v_pk_mul_f32 v[146:147], v[112:113], v[146:147]
	v_exp_f32_e32 v114, v114
	v_exp_f32_e32 v146, v146
	v_exp_f32_e32 v147, v147
	v_exp_f32_e32 v115, v115
	v_add_co_u32_e32 v152, vcc, s62, v110
	v_pk_add_f32 v[146:147], v[146:147], 1.0 op_sel_hi:[1,0]
	v_pk_add_f32 v[114:115], v[114:115], 1.0 op_sel_hi:[1,0]
	v_rcp_f32_e32 v146, v146
	v_rcp_f32_e32 v147, v147
	v_rcp_f32_e32 v114, v114
	v_rcp_f32_e32 v115, v115
	v_addc_co_u32_e32 v153, vcc, 0, v111, vcc
	v_pk_mul_f32 v[112:113], v[112:113], v[146:147]
	v_pk_mul_f32 v[102:103], v[102:103], v[114:115]
	v_pk_mul_f32 v[146:147], v[14:15], v[88:89]
	v_pk_mul_f32 v[170:171], v[26:27], v[96:97]
	v_pk_fma_f32 v[146:147], v[18:19], v[120:121], v[146:147]
	v_pk_fma_f32 v[170:171], v[30:31], v[132:133], v[170:171]
	v_pk_fma_f32 v[146:147], v[22:23], v[92:93], v[146:147]
	s_nop 0
	v_lshlrev_b32_e32 v43, 16, v98
	v_and_b32_e32 v98, 0xffff0000, v98
	v_lshlrev_b32_e32 v114, 16, v99
	v_and_b32_e32 v99, 0xffff0000, v99
	v_mul_f32_e32 v98, v113, v98
	v_mul_f32_e32 v99, v103, v99
	v_mul_f32_e32 v43, v112, v43
	v_mul_f32_e32 v102, v102, v114
	v_cvt_pk_bf16_f32 v98, v43, v98
	v_cvt_pk_bf16_f32 v99, v102, v99
	flat_store_dwordx2 v[148:149], v[98:99] offset:1024
	s_nop 1
	v_mov_b64_e32 v[112:113], v[186:187]
	v_lshlrev_b32_e32 v98, 16, v124
	v_and_b32_e32 v99, 0xffff0000, v124
	v_lshlrev_b32_e32 v102, 16, v125
	v_and_b32_e32 v103, 0xffff0000, v125
	v_pk_mul_f32 v[114:115], v[2:3], v[74:75]
	v_pk_mul_f32 v[124:125], v[0:1], v[70:71]
	v_pk_mul_f32 v[148:149], v[12:13], v[86:87]
	v_pk_fma_f32 v[114:115], v[6:7], v[126:127], v[114:115]
	v_pk_fma_f32 v[124:125], v[4:5], v[122:123], v[124:125]
	v_pk_fma_f32 v[148:149], v[16:17], v[118:119], v[148:149]
	v_pk_fma_f32 v[114:115], v[10:11], v[84:85], v[114:115]
	v_pk_fma_f32 v[124:125], v[8:9], v[82:83], v[124:125]
	v_pk_fma_f32 v[148:149], v[20:21], v[90:91], v[148:149]
	v_pk_add_f32 v[114:115], v[38:39], v[114:115]
	v_pk_add_f32 v[124:125], v[36:37], v[124:125]
	v_pk_fma_f32 v[170:171], v[34:35], v[102:103], v[170:171]
	v_pk_fma_f32 v[172:173], v[32:33], v[98:99], v[172:173]
	v_pk_add_f32 v[114:115], v[114:115], v[146:147]
	v_pk_add_f32 v[124:125], v[124:125], v[148:149]
	v_pk_add_f32 v[114:115], v[114:115], v[170:171]
	v_pk_add_f32 v[124:125], v[124:125], v[172:173]
	v_pk_mul_f32 v[146:147], v[114:115], v[114:115]
	v_pk_mul_f32 v[148:149], v[124:125], v[124:125]
	v_pk_fma_f32 v[146:147], v[146:147], s[26:27], v[150:151] op_sel_hi:[1,0,0] neg_lo:[1,0,0] neg_hi:[1,0,0]
	v_pk_fma_f32 v[148:149], v[148:149], s[26:27], v[150:151] op_sel_hi:[1,0,0] neg_lo:[1,0,0] neg_hi:[1,0,0]
	v_pk_mul_f32 v[146:147], v[114:115], v[146:147]
	v_pk_mul_f32 v[148:149], v[124:125], v[148:149]
	v_exp_f32_e32 v146, v146
	v_exp_f32_e32 v148, v148
	v_exp_f32_e32 v149, v149
	v_exp_f32_e32 v147, v147
	v_add_co_u32_e32 v170, vcc, s62, v100
	v_pk_add_f32 v[148:149], v[148:149], 1.0 op_sel_hi:[1,0]
	v_pk_add_f32 v[146:147], v[146:147], 1.0 op_sel_hi:[1,0]
	v_rcp_f32_e32 v148, v148
	v_rcp_f32_e32 v149, v149
	v_rcp_f32_e32 v146, v146
	v_rcp_f32_e32 v147, v147
	v_addc_co_u32_e32 v171, vcc, 0, v101, vcc
	v_pk_mul_f32 v[124:125], v[124:125], v[148:149]
	v_pk_mul_f32 v[114:115], v[114:115], v[146:147]
	v_mov_b64_e32 v[148:149], v[158:159]
	v_pk_fma_f32 v[158:159], v[30:31], v[140:141], v[174:175]
	v_pk_fma_f32 v[174:175], v[28:29], v[138:139], v[176:177]
	s_nop 0
	v_lshlrev_b32_e32 v43, 16, v112
	v_and_b32_e32 v112, 0xffff0000, v112
	v_lshlrev_b32_e32 v146, 16, v113
	v_and_b32_e32 v113, 0xffff0000, v113
	v_mul_f32_e32 v112, v125, v112
	v_mul_f32_e32 v113, v115, v113
	v_mul_f32_e32 v43, v124, v43
	v_mul_f32_e32 v114, v114, v146
	v_cvt_pk_bf16_f32 v112, v43, v112
	v_cvt_pk_bf16_f32 v113, v114, v113
	flat_store_dwordx2 v[152:153], v[112:113] offset:1024
	s_nop 1
	v_mov_b64_e32 v[172:173], v[188:189]
	v_lshlrev_b32_e32 v112, 16, v104
	v_and_b32_e32 v113, 0xffff0000, v104
	v_lshlrev_b32_e32 v114, 16, v105
	v_and_b32_e32 v115, 0xffff0000, v105
	v_pk_mul_f32 v[104:105], v[2:3], v[88:89]
	v_pk_mul_f32 v[124:125], v[0:1], v[86:87]
	v_pk_mul_f32 v[146:147], v[14:15], v[96:97]
	v_pk_mul_f32 v[152:153], v[12:13], v[94:95]
	v_pk_fma_f32 v[104:105], v[6:7], v[120:121], v[104:105]
	v_pk_fma_f32 v[124:125], v[4:5], v[118:119], v[124:125]
	v_pk_fma_f32 v[146:147], v[18:19], v[132:133], v[146:147]
	v_pk_fma_f32 v[152:153], v[16:17], v[130:131], v[152:153]
	v_pk_fma_f32 v[104:105], v[10:11], v[92:93], v[104:105]
	v_pk_fma_f32 v[124:125], v[8:9], v[90:91], v[124:125]
	v_pk_fma_f32 v[146:147], v[22:23], v[102:103], v[146:147]
	v_pk_fma_f32 v[152:153], v[20:21], v[98:99], v[152:153]
	v_pk_add_f32 v[104:105], v[38:39], v[104:105]
	v_pk_add_f32 v[124:125], v[36:37], v[124:125]
	v_pk_fma_f32 v[158:159], v[34:35], v[114:115], v[158:159]
	v_pk_fma_f32 v[174:175], v[32:33], v[112:113], v[174:175]
	v_pk_add_f32 v[104:105], v[104:105], v[146:147]
	v_pk_add_f32 v[124:125], v[124:125], v[152:153]
	v_pk_add_f32 v[104:105], v[104:105], v[158:159]
	v_pk_add_f32 v[158:159], v[124:125], v[174:175]
	v_pk_mul_f32 v[124:125], v[104:105], v[104:105]
	v_pk_mul_f32 v[146:147], v[158:159], v[158:159]
	v_pk_fma_f32 v[124:125], v[124:125], s[26:27], v[150:151] op_sel_hi:[1,0,0] neg_lo:[1,0,0] neg_hi:[1,0,0]
	v_pk_fma_f32 v[146:147], v[146:147], s[26:27], v[150:151] op_sel_hi:[1,0,0] neg_lo:[1,0,0] neg_hi:[1,0,0]
	v_pk_mul_f32 v[124:125], v[104:105], v[124:125]
	v_pk_mul_f32 v[146:147], v[158:159], v[146:147]
	v_exp_f32_e32 v124, v124
	v_exp_f32_e32 v146, v146
	v_exp_f32_e32 v147, v147
	v_exp_f32_e32 v125, v125
	v_mov_b64_e32 v[152:153], v[154:155]
	v_mov_b64_e32 v[150:151], v[156:157]
	v_pk_add_f32 v[146:147], v[146:147], 1.0 op_sel_hi:[1,0]
	v_pk_add_f32 v[124:125], v[124:125], 1.0 op_sel_hi:[1,0]
	v_rcp_f32_e32 v154, v146
	v_rcp_f32_e32 v155, v147
	v_rcp_f32_e32 v156, v124
	v_rcp_f32_e32 v157, v125
	v_mov_b64_e32 v[146:147], v[160:161]
	v_pk_mul_f32 v[154:155], v[158:159], v[154:155]
	v_mov_b64_e32 v[124:125], v[162:163]
	v_pk_mul_f32 v[104:105], v[104:105], v[156:157]
	s_nop 0
	v_and_b32_e32 v158, 0xffff0000, v173
	v_lshlrev_b32_e32 v43, 16, v172
	v_and_b32_e32 v156, 0xffff0000, v172
	v_lshlrev_b32_e32 v157, 16, v173
	v_mul_f32_e32 v105, v105, v158
	v_mul_f32_e32 v43, v154, v43
	v_mul_f32_e32 v154, v155, v156
	v_mul_f32_e32 v155, v104, v157
	v_cvt_pk_bf16_f32 v104, v43, v154
	v_cvt_pk_bf16_f32 v105, v155, v105
	flat_store_dwordx2 v[170:171], v[104:105] offset:1024
	v_mov_b64_e32 v[104:105], v[164:165]
